# phase 0 static re-balance: GEMV CUs take 3 transposes, the other 64 CUs take 10
# baseline (speedup 1.0000x reference)
; DI void phase_prep(const P& p, char* lds) {
;   for (int it = blockIdx.x; it < 192 + 960 + 256; it += gridDim.x) {
;     if (it < 192) {
;       mod_item(p, it, lds);
.LBB0_942:
	v_readlane_b32 s0, v254, 4
	v_readlane_b32 s1, v254, 5
	s_andn2_b64 vcc, exec, s[0:1]
	v_readlane_b32 s23, v254, 0
	s_cmpk_lt_u32 s23, 0xc0
	s_cbranch_scc1 .Lprep_init_done
	s_mul_i32 s23, s23, 10
	s_addk_i32 s23, 0xf940
.Lprep_init_done:
	s_cbranch_vccz .LBB0_961

; DI void phase_prep(const P& p, char* lds) {
;   for (int it = blockIdx.x; it < 192 + 960 + 256; it += gridDim.x) {
;     if (it < 192) {
;       mod_item(p, it, lds);
;     } else if (it < 192 + 960) {
;       int t = it - 192;
;       int l = t / 480, rem = t % 480;
;       int kt = rem / 30, nt2 = rem % 30;
;       transpose_item(p.w_in + (size_t)l * 1024 * NIN, p.Wt + (size_t)l * NIN * 1024, NIN, kt, nt2, lds);
;     } else {
;       int t = it - 192 - 960;
;       int l = t >> 7, rem = t & 127;
;       int kt = rem >> 3, nt2 = rem & 7;
;       transpose_item(p.w_out + (size_t)l * 1024 * 1024, p.Wot + (size_t)l * 1024 * 1024, 1024, kt, nt2, lds);
;     }
;   }
.LBB0_960:
	v_readlane_b32 s0, v254, 0
	s_cmpk_gt_i32 s23, 0xbf
	s_cbranch_scc1 .Lprep_next_tr
	s_mul_i32 s23, s23, 3
	s_addk_i32 s23, 0x340
	s_branch .LBB0_961
.Lprep_next_tr:
	s_add_i32 s23, s23, 1
	s_mul_i32 s1, s0, 3
	s_addk_i32 s1, 0x343
	s_mul_i32 s2, s0, 10
	s_addk_i32 s2, 0xf94a
	s_cmpk_lt_u32 s0, 0xc0
	s_cselect_b32 s1, s1, s2
	s_cmp_ge_i32 s23, s1
	s_cbranch_scc1 .LBB0_943
